# phase B prompt side: blocks with one conv item run the SSM chunk-state items first and their conv item afterwards, so the two-conv blocks get the early HBM bandwidth (same work, reordered)
# speedup vs baseline: 1.0454x; 1.0045x over previous
.LBB0_299:
	s_or_b64 exec, exec, s[0:1]
	s_xor_b64 s[0:1], s[4:5], -1
	v_writelane_b32 v234, s0, 59
	s_waitcnt lgkmcnt(0)
	s_barrier
	v_writelane_b32 v234, s1, 60
	s_xor_b64 s[0:1], s[78:79], -1
	v_writelane_b32 v234, s0, 61
	s_nop 1
	v_writelane_b32 v234, s1, 62
	s_and_b64 s[0:1], s[78:79], exec
	s_cselect_b32 s59, 32, 48
	s_cmp_ge_i32 s2, s59
	s_mov_b64 s[0:1], -1
	s_cbranch_scc0 .LBB0_373
	s_sub_i32 s7, 0x100, s59
	s_sub_i32 s6, s2, s59
	s_mov_b32 s98, 0
	s_cmpk_gt_u32 s6, 0xff
	s_cbranch_scc1 .LBB0_319
	s_cmp_lt_u32 s6, s59
	s_cbranch_scc1 .Lmy_conv_go
	s_mov_b32 s98, 1
	s_branch .LBB0_319
.Lmy_conv_go:
	v_readlane_b32 s0, v234, 48
	v_readlane_b32 s1, v234, 49
	s_mul_i32 s94, s0, 0xc00
	v_readlane_b32 s16, v237, 40
	s_mov_b32 s12, s0
	s_lshl_b64 s[0:1], s[94:95], 2
	v_readlane_b32 s20, v237, 44
	v_readlane_b32 s21, v237, 45
	s_add_u32 s4, s20, s0
	s_addc_u32 s5, s21, s1
	s_lshl_b32 s94, s12, 10
	v_readlane_b32 s22, v237, 46
	s_lshl_b64 s[0:1], s[94:95], 2
	v_readlane_b32 s18, v237, 42
	v_readlane_b32 s23, v237, 47
	v_readlane_b32 s30, v237, 54
	v_readlane_b32 s31, v237, 55
	s_add_u32 s8, s22, s0
	v_readlane_b32 s19, v237, 43
	v_readlane_b32 s30, v237, 2
	s_addc_u32 s9, s23, s1
	s_lshl_b32 s18, s12, 4
	s_lshl_b32 s0, s12, 11
	v_readlane_b32 s31, v237, 3
	v_readlane_b32 s10, v237, 0
	s_or_b32 s19, s18, 0xffffffe2
	s_or_b32 s20, s0, 0x1040000
	s_or_b32 s21, s0, 0x1040400
	s_mov_b32 s22, s6
	v_readlane_b32 s17, v237, 41
	v_readlane_b32 s24, v237, 48
	v_readlane_b32 s25, v237, 49
	v_readlane_b32 s26, v237, 50
	v_readlane_b32 s27, v237, 51
	v_readlane_b32 s28, v237, 52
	v_readlane_b32 s29, v237, 53
	v_readlane_b32 s11, v237, 1
	s_branch .LBB0_303

.LBB0_319:
	s_cmp_eq_u32 s98, 2
	s_cbranch_scc1 .LBB0_333
	v_mov_b32_e32 v0, v194
	s_and_b64 s[0:1], s[78:79], exec
	s_movk_i32 s0, 0xffe0
	v_readfirstlane_b32 s1, v0
	v_cvt_f32_u32_e32 v0, s7
	s_cselect_b32 s0, s0, 0xffffffd0
	s_sub_i32 s4, 0, s7
	s_add_i32 s0, s7, s0
	v_rcp_iflag_f32_e32 v0, v0
	s_add_i32 s0, s0, s6
	s_ashr_i32 s1, s1, 6
	v_mul_f32_e32 v0, 0x4f7ffffe, v0
	v_cvt_u32_f32_e32 v0, v0
	s_nop 0
	v_readfirstlane_b32 s5, v0
	s_mul_i32 s4, s4, s5
	s_mul_hi_u32 s4, s5, s4
	s_add_i32 s5, s5, s4
	s_mul_hi_u32 s4, s0, s5
	s_mul_i32 s4, s4, s7
	s_sub_i32 s0, s0, s4
	s_sub_i32 s4, s0, s7
	s_cmp_ge_u32 s0, s7
	s_cselect_b32 s0, s4, s0
	s_sub_i32 s4, s0, s7
	s_cmp_ge_u32 s0, s7
	s_cselect_b32 s18, s4, s0
	v_readlane_b32 s4, v234, 48
	s_mul_i32 s0, s4, 0x98000
	v_readlane_b32 s4, v235, 2
	v_readlane_b32 s5, v234, 49
	s_add_u32 s4, s4, s0
	v_readlane_b32 s0, v235, 3
	s_addc_u32 s5, s0, 0
	s_add_u32 s8, s4, 0x18000
	s_addc_u32 s9, s5, 0
	s_lshl_b32 s0, s18, 3
	s_add_i32 s19, s1, s0
	s_lshl_b32 s0, s59, 3
	s_sub_i32 s20, 0x800, s0
	s_branch .LBB0_321

.LBB0_333:
	s_cmp_eq_u32 s98, 1
	s_cbranch_scc0 .Lmy_post_go
	s_mov_b32 s98, 2
	s_branch .Lmy_conv_go
